# grid barrier: early inv + pre-clean wbl2 by every 4th local arriver (remaining 4,8,..,28)
# baseline (speedup 1.0000x reference)
.LBB0_141:
	s_or_b64 exec, exec, s[8:9]
	v_cvt_f32_u32_e32 v4, v2
	s_waitcnt vmcnt(0)
	buffer_inv sc1
	v_readfirstlane_b32 s6, v3
	v_sub_u32_e32 v3, 0, v2
	v_rcp_iflag_f32_e32 v4, v4
	v_add_u32_e32 v5, s6, v1
	v_mul_f32_e32 v4, 0x4f7ffffe, v4
	v_cvt_u32_f32_e32 v4, v4
	v_mul_lo_u32 v1, v3, v4
	v_mul_hi_u32 v1, v4, v1
	v_add_u32_e32 v1, v4, v1
	v_mul_hi_u32 v1, v5, v1
	v_mul_lo_u32 v3, v1, v2
	v_sub_u32_e32 v3, v5, v3
	v_add_u32_e32 v4, 1, v1
	v_cmp_ge_u32_e32 vcc, v3, v2
	s_nop 1
	v_cndmask_b32_e32 v1, v1, v4, vcc
	v_sub_u32_e32 v4, v3, v2
	v_cndmask_b32_e32 v3, v3, v4, vcc
	v_add_u32_e32 v4, 1, v1
	v_cmp_ge_u32_e32 vcc, v3, v2
	v_add_u32_e32 v3, 1, v5
	s_nop 0
	v_cndmask_b32_e32 v1, v1, v4, vcc
	v_mul_lo_u32 v4, v2, v1
	v_add_u32_e32 v2, v4, v2
	v_sub_u32_e32 v4, v2, v3
	v_add_u32_e32 v4, -1, v4
	v_and_b32_e32 v4, 0x80000003, v4
	v_cmp_eq_u32_e32 vcc, 3, v4
	s_cbranch_vccz .Lnopre_0
	buffer_wbl2 sc1

.LBB0_481:
	s_or_b64 exec, exec, s[16:17]
	v_cvt_f32_u32_e32 v4, v2
	s_waitcnt vmcnt(0)
	buffer_inv sc1
	v_readfirstlane_b32 s6, v3
	v_sub_u32_e32 v3, 0, v2
	v_rcp_iflag_f32_e32 v4, v4
	v_add_u32_e32 v5, s6, v1
	v_mul_f32_e32 v4, 0x4f7ffffe, v4
	v_cvt_u32_f32_e32 v4, v4
	v_mul_lo_u32 v1, v3, v4
	v_mul_hi_u32 v1, v4, v1
	v_add_u32_e32 v1, v4, v1
	v_mul_hi_u32 v1, v5, v1
	v_mul_lo_u32 v3, v1, v2
	v_sub_u32_e32 v3, v5, v3
	v_add_u32_e32 v4, 1, v1
	v_cmp_ge_u32_e32 vcc, v3, v2
	s_nop 1
	v_cndmask_b32_e32 v1, v1, v4, vcc
	v_sub_u32_e32 v4, v3, v2
	v_cndmask_b32_e32 v3, v3, v4, vcc
	v_add_u32_e32 v4, 1, v1
	v_cmp_ge_u32_e32 vcc, v3, v2
	v_add_u32_e32 v3, 1, v5
	s_nop 0
	v_cndmask_b32_e32 v1, v1, v4, vcc
	v_mul_lo_u32 v4, v2, v1
	v_add_u32_e32 v2, v4, v2
	v_sub_u32_e32 v4, v2, v3
	v_add_u32_e32 v4, -1, v4
	v_and_b32_e32 v4, 0x80000003, v4
	v_cmp_eq_u32_e32 vcc, 3, v4
	s_cbranch_vccz .Lnopre_5
	buffer_wbl2 sc1

.LBB0_626:
	s_or_b64 exec, exec, s[10:11]
	v_cvt_f32_u32_e32 v4, v2
	s_waitcnt vmcnt(0)
	buffer_inv sc1
	v_readfirstlane_b32 s8, v3
	v_sub_u32_e32 v3, 0, v2
	v_rcp_iflag_f32_e32 v4, v4
	v_add_u32_e32 v5, s8, v1
	v_mul_f32_e32 v4, 0x4f7ffffe, v4
	v_cvt_u32_f32_e32 v4, v4
	v_mul_lo_u32 v1, v3, v4
	v_mul_hi_u32 v1, v4, v1
	v_add_u32_e32 v1, v4, v1
	v_mul_hi_u32 v1, v5, v1
	v_mul_lo_u32 v3, v1, v2
	v_sub_u32_e32 v3, v5, v3
	v_add_u32_e32 v4, 1, v1
	v_cmp_ge_u32_e32 vcc, v3, v2
	s_nop 1
	v_cndmask_b32_e32 v1, v1, v4, vcc
	v_sub_u32_e32 v4, v3, v2
	v_cndmask_b32_e32 v3, v3, v4, vcc
	v_add_u32_e32 v4, 1, v1
	v_cmp_ge_u32_e32 vcc, v3, v2
	v_add_u32_e32 v3, 1, v5
	s_nop 0
	v_cndmask_b32_e32 v1, v1, v4, vcc
	v_mul_lo_u32 v4, v2, v1
	v_add_u32_e32 v2, v4, v2
	v_sub_u32_e32 v4, v2, v3
	v_add_u32_e32 v4, -1, v4
	v_and_b32_e32 v4, 0x80000003, v4
	v_cmp_eq_u32_e32 vcc, 3, v4
	s_cbranch_vccz .Lnopre_7
	buffer_wbl2 sc1

.LBB0_681:
	s_or_b64 exec, exec, s[12:13]
	v_cvt_f32_u32_e32 v4, v2
	s_waitcnt vmcnt(0)
	buffer_inv sc1
	v_readfirstlane_b32 s10, v3
	v_sub_u32_e32 v3, 0, v2
	v_rcp_iflag_f32_e32 v4, v4
	v_add_u32_e32 v5, s10, v1
	v_mul_f32_e32 v4, 0x4f7ffffe, v4
	v_cvt_u32_f32_e32 v4, v4
	v_mul_lo_u32 v1, v3, v4
	v_mul_hi_u32 v1, v4, v1
	v_add_u32_e32 v1, v4, v1
	v_mul_hi_u32 v1, v5, v1
	v_mul_lo_u32 v3, v1, v2
	v_sub_u32_e32 v3, v5, v3
	v_add_u32_e32 v4, 1, v1
	v_cmp_ge_u32_e32 vcc, v3, v2
	s_nop 1
	v_cndmask_b32_e32 v1, v1, v4, vcc
	v_sub_u32_e32 v4, v3, v2
	v_cndmask_b32_e32 v3, v3, v4, vcc
	v_add_u32_e32 v4, 1, v1
	v_cmp_ge_u32_e32 vcc, v3, v2
	v_add_u32_e32 v3, 1, v5
	s_nop 0
	v_cndmask_b32_e32 v1, v1, v4, vcc
	v_mul_lo_u32 v4, v2, v1
	v_add_u32_e32 v2, v4, v2
	v_sub_u32_e32 v4, v2, v3
	v_add_u32_e32 v4, -1, v4
	v_and_b32_e32 v4, 0x80000003, v4
	v_cmp_eq_u32_e32 vcc, 3, v4
	s_cbranch_vccz .Lnopre_8
	buffer_wbl2 sc1

.LBB0_749:
	s_or_b64 exec, exec, s[16:17]
	v_cvt_f32_u32_e32 v4, v2
	s_waitcnt vmcnt(0)
	buffer_inv sc1
	v_readfirstlane_b32 s12, v3
	v_sub_u32_e32 v3, 0, v2
	v_rcp_iflag_f32_e32 v4, v4
	v_add_u32_e32 v5, s12, v1
	v_mul_f32_e32 v4, 0x4f7ffffe, v4
	v_cvt_u32_f32_e32 v4, v4
	v_mul_lo_u32 v1, v3, v4
	v_mul_hi_u32 v1, v4, v1
	v_add_u32_e32 v1, v4, v1
	v_mul_hi_u32 v1, v5, v1
	v_mul_lo_u32 v3, v1, v2
	v_sub_u32_e32 v3, v5, v3
	v_add_u32_e32 v4, 1, v1
	v_cmp_ge_u32_e32 vcc, v3, v2
	s_nop 1
	v_cndmask_b32_e32 v1, v1, v4, vcc
	v_sub_u32_e32 v4, v3, v2
	v_cndmask_b32_e32 v3, v3, v4, vcc
	v_add_u32_e32 v4, 1, v1
	v_cmp_ge_u32_e32 vcc, v3, v2
	v_add_u32_e32 v3, 1, v5
	s_nop 0
	v_cndmask_b32_e32 v1, v1, v4, vcc
	v_mul_lo_u32 v4, v2, v1
	v_add_u32_e32 v2, v4, v2
	v_sub_u32_e32 v4, v2, v3
	v_add_u32_e32 v4, -1, v4
	v_and_b32_e32 v4, 0x80000003, v4
	v_cmp_eq_u32_e32 vcc, 3, v4
	s_cbranch_vccz .Lnopre_9
	buffer_wbl2 sc1
